# P2 in-proj GEMM main loop hand-rescheduled: barrier moved mid k-tile, rolling in-place fragment refill, LDS-DMA issue interleaved with MFMAs
# speedup vs baseline: 1.0204x; 1.0204x over previous
.LBB0_167:
	s_lshl_b32 s7, s45, 7
	s_add_u32 s14, s2, s7
	s_addc_u32 s15, s3, 0
	s_add_u32 s12, s0, s7
	s_addc_u32 s13, s1, 0
	v_readfirstlane_b32 s16, v147
	v_add_u32_e32 v0, v158, v159
	v_add_u32_e32 v177, v146, v160
	s_mov_b32 m0, s16
	s_cmp_eq_u32 s46, 0
	s_cbranch_scc1 .Lp2_first
	ds_read_b128 v[238:241], v177 offset:32768
	v_mfma_f32_16x16x32_bf16 v[122:125], v[242:245], v[178:181], v[122:125]
	global_load_lds_dwordx4 v130, s[14:15]
	s_add_u32 m0, m0, 0x2000
	v_mfma_f32_16x16x32_bf16 v[106:109], v[242:245], v[182:185], v[106:109]
	v_mfma_f32_16x16x32_bf16 v[90:93], v[242:245], v[186:189], v[90:93]
	v_mfma_f32_16x16x32_bf16 v[74:77], v[242:245], v[190:193], v[74:77]
	v_mfma_f32_16x16x32_bf16 v[58:61], v[242:245], v[222:225], v[58:61]
	v_mfma_f32_16x16x32_bf16 v[42:45], v[242:245], v[226:229], v[42:45]
	v_mfma_f32_16x16x32_bf16 v[26:29], v[242:245], v[230:233], v[26:29]
	global_load_lds_dwordx4 v132, s[14:15]
	s_add_u32 m0, m0, 0x2000
	v_mfma_f32_16x16x32_bf16 v[10:13], v[242:245], v[234:237], v[10:13]
	ds_read_b128 v[242:245], v177 offset:34816
	v_mfma_f32_16x16x32_bf16 v[118:121], v[246:249], v[178:181], v[118:121]
	v_mfma_f32_16x16x32_bf16 v[114:117], v[212:215], v[178:181], v[114:117]
	ds_read_b128 v[178:181], v162
	v_mfma_f32_16x16x32_bf16 v[102:105], v[246:249], v[182:185], v[102:105]
	v_mfma_f32_16x16x32_bf16 v[98:101], v[212:215], v[182:185], v[98:101]
	ds_read_b128 v[182:185], v163
	v_mfma_f32_16x16x32_bf16 v[86:89], v[246:249], v[186:189], v[86:89]
	global_load_lds_dwordx4 v134, s[14:15]
	s_add_u32 m0, m0, 0x2000
	v_mfma_f32_16x16x32_bf16 v[82:85], v[212:215], v[186:189], v[82:85]
	ds_read_b128 v[186:189], v164
	v_mfma_f32_16x16x32_bf16 v[70:73], v[246:249], v[190:193], v[70:73]
	v_mfma_f32_16x16x32_bf16 v[66:69], v[212:215], v[190:193], v[66:69]
	ds_read_b128 v[190:193], v165
	v_mfma_f32_16x16x32_bf16 v[54:57], v[246:249], v[222:225], v[54:57]
	v_mfma_f32_16x16x32_bf16 v[50:53], v[212:215], v[222:225], v[50:53]
	ds_read_b128 v[222:225], v166
	v_mfma_f32_16x16x32_bf16 v[38:41], v[246:249], v[226:229], v[38:41]
	global_load_lds_dwordx4 v136, s[14:15]
	s_add_u32 m0, m0, 0x2000
	v_mfma_f32_16x16x32_bf16 v[34:37], v[212:215], v[226:229], v[34:37]
	ds_read_b128 v[226:229], v167
	v_mfma_f32_16x16x32_bf16 v[22:25], v[246:249], v[230:233], v[22:25]
	v_mfma_f32_16x16x32_bf16 v[18:21], v[212:215], v[230:233], v[18:21]
	ds_read_b128 v[230:233], v168
	v_mfma_f32_16x16x32_bf16 v[6:9], v[246:249], v[234:237], v[6:9]
	v_mfma_f32_16x16x32_bf16 v[2:5], v[212:215], v[234:237], v[2:5]
	ds_read_b128 v[234:237], v0
	ds_read_b128 v[246:249], v177 offset:36864
	ds_read_b128 v[212:215], v177 offset:38912
	s_add_i32 s6, s6, 1
	s_cmp_lg_u32 s6, 32
	s_cbranch_scc0 .Lp2_epi0
.Lp2_cont0:
	s_cmp_ge_i32 s46, s91
	s_cbranch_scc1 .Lp2_exit
.Lp2_partb0:
	s_waitcnt lgkmcnt(9)
	v_mfma_f32_16x16x32_bf16 v[126:129], v[238:241], v[178:181], v[126:129]
	global_load_lds_dwordx4 v130, s[12:13]
	s_add_u32 m0, m0, 0x2000
	s_waitcnt lgkmcnt(8)
	v_mfma_f32_16x16x32_bf16 v[110:113], v[238:241], v[182:185], v[110:113]
	s_waitcnt lgkmcnt(7)
	v_mfma_f32_16x16x32_bf16 v[94:97], v[238:241], v[186:189], v[94:97]
	s_waitcnt lgkmcnt(6)
	v_mfma_f32_16x16x32_bf16 v[78:81], v[238:241], v[190:193], v[78:81]
	s_waitcnt lgkmcnt(5)
	v_mfma_f32_16x16x32_bf16 v[62:65], v[238:241], v[222:225], v[62:65]
	s_waitcnt lgkmcnt(4)
	v_mfma_f32_16x16x32_bf16 v[46:49], v[238:241], v[226:229], v[46:49]
	s_waitcnt lgkmcnt(3)
	v_mfma_f32_16x16x32_bf16 v[30:33], v[238:241], v[230:233], v[30:33]
	global_load_lds_dwordx4 v132, s[12:13]
	s_add_u32 m0, m0, 0x2000
	s_waitcnt lgkmcnt(2)
	v_mfma_f32_16x16x32_bf16 v[14:17], v[238:241], v[234:237], v[14:17]
	ds_read_b128 v[238:241], v177 offset:33792
	v_mfma_f32_16x16x32_bf16 v[122:125], v[242:245], v[178:181], v[122:125]
	v_mfma_f32_16x16x32_bf16 v[106:109], v[242:245], v[182:185], v[106:109]
	v_mfma_f32_16x16x32_bf16 v[90:93], v[242:245], v[186:189], v[90:93]
	v_mfma_f32_16x16x32_bf16 v[74:77], v[242:245], v[190:193], v[74:77]
	v_mfma_f32_16x16x32_bf16 v[58:61], v[242:245], v[222:225], v[58:61]
	global_load_lds_dwordx4 v134, s[12:13]
	s_add_u32 m0, m0, 0x2000
	v_mfma_f32_16x16x32_bf16 v[42:45], v[242:245], v[226:229], v[42:45]
	v_mfma_f32_16x16x32_bf16 v[26:29], v[242:245], v[230:233], v[26:29]
	v_mfma_f32_16x16x32_bf16 v[10:13], v[242:245], v[234:237], v[10:13]
	ds_read_b128 v[242:245], v177 offset:35840
	s_waitcnt lgkmcnt(3)
	v_mfma_f32_16x16x32_bf16 v[118:121], v[246:249], v[178:181], v[118:121]
	s_waitcnt lgkmcnt(2)
	v_mfma_f32_16x16x32_bf16 v[114:117], v[212:215], v[178:181], v[114:117]
	ds_read_b128 v[178:181], v162 offset:1024
	v_mfma_f32_16x16x32_bf16 v[102:105], v[246:249], v[182:185], v[102:105]
	global_load_lds_dwordx4 v136, s[12:13]
	v_mfma_f32_16x16x32_bf16 v[98:101], v[212:215], v[182:185], v[98:101]
	ds_read_b128 v[182:185], v163 offset:1024
	v_mfma_f32_16x16x32_bf16 v[86:89], v[246:249], v[186:189], v[86:89]
	v_mfma_f32_16x16x32_bf16 v[82:85], v[212:215], v[186:189], v[82:85]
	ds_read_b128 v[186:189], v164 offset:1024
	v_mfma_f32_16x16x32_bf16 v[70:73], v[246:249], v[190:193], v[70:73]
	v_mfma_f32_16x16x32_bf16 v[66:69], v[212:215], v[190:193], v[66:69]
	ds_read_b128 v[190:193], v165 offset:1024
	v_mfma_f32_16x16x32_bf16 v[54:57], v[246:249], v[222:225], v[54:57]
	v_mfma_f32_16x16x32_bf16 v[50:53], v[212:215], v[222:225], v[50:53]
	ds_read_b128 v[222:225], v166 offset:1024
	v_mfma_f32_16x16x32_bf16 v[38:41], v[246:249], v[226:229], v[38:41]
	v_mfma_f32_16x16x32_bf16 v[34:37], v[212:215], v[226:229], v[34:37]
	ds_read_b128 v[226:229], v167 offset:1024
	v_mfma_f32_16x16x32_bf16 v[22:25], v[246:249], v[230:233], v[22:25]
	v_mfma_f32_16x16x32_bf16 v[18:21], v[212:215], v[230:233], v[18:21]
	ds_read_b128 v[230:233], v168 offset:1024
	v_mfma_f32_16x16x32_bf16 v[6:9], v[246:249], v[234:237], v[6:9]
	v_mfma_f32_16x16x32_bf16 v[2:5], v[212:215], v[234:237], v[2:5]
	ds_read_b128 v[234:237], v0 offset:1024
	ds_read_b128 v[246:249], v177 offset:37888
	ds_read_b128 v[212:215], v177 offset:39936
	s_waitcnt lgkmcnt(9)
	v_mfma_f32_16x16x32_bf16 v[126:129], v[238:241], v[178:181], v[126:129]
	s_waitcnt lgkmcnt(8)
	v_mfma_f32_16x16x32_bf16 v[110:113], v[238:241], v[182:185], v[110:113]
	s_waitcnt lgkmcnt(7)
	v_mfma_f32_16x16x32_bf16 v[94:97], v[238:241], v[186:189], v[94:97]
	s_waitcnt lgkmcnt(6)
	v_mfma_f32_16x16x32_bf16 v[78:81], v[238:241], v[190:193], v[78:81]
	s_waitcnt lgkmcnt(5)
	v_mfma_f32_16x16x32_bf16 v[62:65], v[238:241], v[222:225], v[62:65]
	s_waitcnt lgkmcnt(4)
	v_mfma_f32_16x16x32_bf16 v[46:49], v[238:241], v[226:229], v[46:49]
	s_waitcnt lgkmcnt(3)
	v_mfma_f32_16x16x32_bf16 v[30:33], v[238:241], v[230:233], v[30:33]
	s_waitcnt lgkmcnt(2)
	v_mfma_f32_16x16x32_bf16 v[14:17], v[238:241], v[234:237], v[14:17]
	s_add_i32 s45, s45, 1
	s_cmp_lg_u32 s45, 32
	s_cbranch_scc1 .Lp2_nowrap0
	s_add_i32 s22, s22, 1
	s_cmp_ge_i32 s22, s57
	s_cbranch_scc1 .Lp2_segdone0
	s_mul_i32 s0, s22, s62
	s_add_i32 s1, s0, s86
	s_mul_hi_i32 s0, s1, 0x2aaaaaab
	s_lshr_b32 s2, s0, 31
	s_ashr_i32 s0, s0, 3
	s_add_i32 s0, s0, s2
	s_mul_i32 s2, s0, 48
	s_sub_i32 s2, s1, s2
	s_ashr_i32 s3, s2, 31
	s_ashr_i32 s1, s0, 31
	s_lshl_b64 s[2:3], s[2:3], 20
	s_lshl_b64 s[0:1], s[0:1], 20
	v_readlane_b32 s12, v254, 3
	v_readlane_b32 s13, v254, 4
	s_add_u32 s2, s12, s2
	s_addc_u32 s3, s13, s3
	s_add_u32 s0, s11, s0
	s_addc_u32 s1, s21, s1

.Lp2_nowrap0:
	s_waitcnt vmcnt(0) lgkmcnt(0)
	s_barrier
	s_add_i32 s46, s46, 1
.Lp2_body1:
	s_lshl_b32 s7, s45, 7
	s_add_u32 s14, s2, s7
	s_addc_u32 s15, s3, 0
	s_add_u32 s12, s0, s7
	s_addc_u32 s13, s1, 0
	v_readfirstlane_b32 s16, v138
	v_add_u32_e32 v0, v161, v157
	s_mov_b32 m0, s16
	ds_read_b128 v[238:241], v176
	v_mfma_f32_16x16x32_bf16 v[122:125], v[242:245], v[178:181], v[122:125]
	global_load_lds_dwordx4 v130, s[14:15]
	s_add_u32 m0, m0, 0x2000
	v_mfma_f32_16x16x32_bf16 v[106:109], v[242:245], v[182:185], v[106:109]
	v_mfma_f32_16x16x32_bf16 v[90:93], v[242:245], v[186:189], v[90:93]
	v_mfma_f32_16x16x32_bf16 v[74:77], v[242:245], v[190:193], v[74:77]
	v_mfma_f32_16x16x32_bf16 v[58:61], v[242:245], v[222:225], v[58:61]
	v_mfma_f32_16x16x32_bf16 v[42:45], v[242:245], v[226:229], v[42:45]
	v_mfma_f32_16x16x32_bf16 v[26:29], v[242:245], v[230:233], v[26:29]
	global_load_lds_dwordx4 v132, s[14:15]
	s_add_u32 m0, m0, 0x2000
	v_mfma_f32_16x16x32_bf16 v[10:13], v[242:245], v[234:237], v[10:13]
	ds_read_b128 v[242:245], v176 offset:2048
	v_mfma_f32_16x16x32_bf16 v[118:121], v[246:249], v[178:181], v[118:121]
	v_mfma_f32_16x16x32_bf16 v[114:117], v[212:215], v[178:181], v[114:117]
	ds_read_b128 v[178:181], v169
	v_mfma_f32_16x16x32_bf16 v[102:105], v[246:249], v[182:185], v[102:105]
	v_mfma_f32_16x16x32_bf16 v[98:101], v[212:215], v[182:185], v[98:101]
	ds_read_b128 v[182:185], v0
	v_mfma_f32_16x16x32_bf16 v[86:89], v[246:249], v[186:189], v[86:89]
	global_load_lds_dwordx4 v134, s[14:15]
	s_add_u32 m0, m0, 0x2000
	v_mfma_f32_16x16x32_bf16 v[82:85], v[212:215], v[186:189], v[82:85]
	ds_read_b128 v[186:189], v170
	v_mfma_f32_16x16x32_bf16 v[70:73], v[246:249], v[190:193], v[70:73]
	v_mfma_f32_16x16x32_bf16 v[66:69], v[212:215], v[190:193], v[66:69]
	ds_read_b128 v[190:193], v171
	v_mfma_f32_16x16x32_bf16 v[54:57], v[246:249], v[222:225], v[54:57]
	v_mfma_f32_16x16x32_bf16 v[50:53], v[212:215], v[222:225], v[50:53]
	ds_read_b128 v[222:225], v172
	v_mfma_f32_16x16x32_bf16 v[38:41], v[246:249], v[226:229], v[38:41]
	global_load_lds_dwordx4 v136, s[14:15]
	s_add_u32 m0, m0, 0x2000
	v_mfma_f32_16x16x32_bf16 v[34:37], v[212:215], v[226:229], v[34:37]
	ds_read_b128 v[226:229], v173
	v_mfma_f32_16x16x32_bf16 v[22:25], v[246:249], v[230:233], v[22:25]
	v_mfma_f32_16x16x32_bf16 v[18:21], v[212:215], v[230:233], v[18:21]
	ds_read_b128 v[230:233], v174
	v_mfma_f32_16x16x32_bf16 v[6:9], v[246:249], v[234:237], v[6:9]
	v_mfma_f32_16x16x32_bf16 v[2:5], v[212:215], v[234:237], v[2:5]
	ds_read_b128 v[234:237], v175
	ds_read_b128 v[246:249], v176 offset:4096
	ds_read_b128 v[212:215], v176 offset:6144
	s_add_i32 s6, s6, 1
	s_cmp_lg_u32 s6, 32
	s_cbranch_scc0 .Lp2_epi1

.Lp2_partb1:
	s_waitcnt lgkmcnt(9)
	v_mfma_f32_16x16x32_bf16 v[126:129], v[238:241], v[178:181], v[126:129]
	global_load_lds_dwordx4 v130, s[12:13]
	s_add_u32 m0, m0, 0x2000
	s_waitcnt lgkmcnt(8)
	v_mfma_f32_16x16x32_bf16 v[110:113], v[238:241], v[182:185], v[110:113]
	s_waitcnt lgkmcnt(7)
	v_mfma_f32_16x16x32_bf16 v[94:97], v[238:241], v[186:189], v[94:97]
	s_waitcnt lgkmcnt(6)
	v_mfma_f32_16x16x32_bf16 v[78:81], v[238:241], v[190:193], v[78:81]
	s_waitcnt lgkmcnt(5)
	v_mfma_f32_16x16x32_bf16 v[62:65], v[238:241], v[222:225], v[62:65]
	s_waitcnt lgkmcnt(4)
	v_mfma_f32_16x16x32_bf16 v[46:49], v[238:241], v[226:229], v[46:49]
	s_waitcnt lgkmcnt(3)
	v_mfma_f32_16x16x32_bf16 v[30:33], v[238:241], v[230:233], v[30:33]
	global_load_lds_dwordx4 v132, s[12:13]
	s_add_u32 m0, m0, 0x2000
	s_waitcnt lgkmcnt(2)
	v_mfma_f32_16x16x32_bf16 v[14:17], v[238:241], v[234:237], v[14:17]
	ds_read_b128 v[238:241], v176 offset:1024
	v_mfma_f32_16x16x32_bf16 v[122:125], v[242:245], v[178:181], v[122:125]
	v_mfma_f32_16x16x32_bf16 v[106:109], v[242:245], v[182:185], v[106:109]
	v_mfma_f32_16x16x32_bf16 v[90:93], v[242:245], v[186:189], v[90:93]
	v_mfma_f32_16x16x32_bf16 v[74:77], v[242:245], v[190:193], v[74:77]
	v_mfma_f32_16x16x32_bf16 v[58:61], v[242:245], v[222:225], v[58:61]
	global_load_lds_dwordx4 v134, s[12:13]
	s_add_u32 m0, m0, 0x2000
	v_mfma_f32_16x16x32_bf16 v[42:45], v[242:245], v[226:229], v[42:45]
	v_mfma_f32_16x16x32_bf16 v[26:29], v[242:245], v[230:233], v[26:29]
	v_mfma_f32_16x16x32_bf16 v[10:13], v[242:245], v[234:237], v[10:13]
	ds_read_b128 v[242:245], v176 offset:3072
	s_waitcnt lgkmcnt(3)
	v_mfma_f32_16x16x32_bf16 v[118:121], v[246:249], v[178:181], v[118:121]
	s_waitcnt lgkmcnt(2)
	v_mfma_f32_16x16x32_bf16 v[114:117], v[212:215], v[178:181], v[114:117]
	ds_read_b128 v[178:181], v169 offset:1024
	v_mfma_f32_16x16x32_bf16 v[102:105], v[246:249], v[182:185], v[102:105]
	global_load_lds_dwordx4 v136, s[12:13]
	v_mfma_f32_16x16x32_bf16 v[98:101], v[212:215], v[182:185], v[98:101]
	ds_read_b128 v[182:185], v0 offset:1024
	v_mfma_f32_16x16x32_bf16 v[86:89], v[246:249], v[186:189], v[86:89]
	v_mfma_f32_16x16x32_bf16 v[82:85], v[212:215], v[186:189], v[82:85]
	ds_read_b128 v[186:189], v170 offset:1024
	v_mfma_f32_16x16x32_bf16 v[70:73], v[246:249], v[190:193], v[70:73]
	v_mfma_f32_16x16x32_bf16 v[66:69], v[212:215], v[190:193], v[66:69]
	ds_read_b128 v[190:193], v171 offset:1024
	v_mfma_f32_16x16x32_bf16 v[54:57], v[246:249], v[222:225], v[54:57]
	v_mfma_f32_16x16x32_bf16 v[50:53], v[212:215], v[222:225], v[50:53]
	ds_read_b128 v[222:225], v172 offset:1024
	v_mfma_f32_16x16x32_bf16 v[38:41], v[246:249], v[226:229], v[38:41]
	v_mfma_f32_16x16x32_bf16 v[34:37], v[212:215], v[226:229], v[34:37]
	ds_read_b128 v[226:229], v173 offset:1024
	v_mfma_f32_16x16x32_bf16 v[22:25], v[246:249], v[230:233], v[22:25]
	v_mfma_f32_16x16x32_bf16 v[18:21], v[212:215], v[230:233], v[18:21]
	ds_read_b128 v[230:233], v174 offset:1024
	v_mfma_f32_16x16x32_bf16 v[6:9], v[246:249], v[234:237], v[6:9]
	v_mfma_f32_16x16x32_bf16 v[2:5], v[212:215], v[234:237], v[2:5]
	ds_read_b128 v[234:237], v175 offset:1024
	ds_read_b128 v[246:249], v176 offset:5120
	ds_read_b128 v[212:215], v176 offset:7168
	s_waitcnt lgkmcnt(9)
	v_mfma_f32_16x16x32_bf16 v[126:129], v[238:241], v[178:181], v[126:129]
	s_waitcnt lgkmcnt(8)
	v_mfma_f32_16x16x32_bf16 v[110:113], v[238:241], v[182:185], v[110:113]
	s_waitcnt lgkmcnt(7)
	v_mfma_f32_16x16x32_bf16 v[94:97], v[238:241], v[186:189], v[94:97]
	s_waitcnt lgkmcnt(6)
	v_mfma_f32_16x16x32_bf16 v[78:81], v[238:241], v[190:193], v[78:81]
	s_waitcnt lgkmcnt(5)
	v_mfma_f32_16x16x32_bf16 v[62:65], v[238:241], v[222:225], v[62:65]
	s_waitcnt lgkmcnt(4)
	v_mfma_f32_16x16x32_bf16 v[46:49], v[238:241], v[226:229], v[46:49]
	s_waitcnt lgkmcnt(3)
	v_mfma_f32_16x16x32_bf16 v[30:33], v[238:241], v[230:233], v[30:33]
	s_waitcnt lgkmcnt(2)
	v_mfma_f32_16x16x32_bf16 v[14:17], v[238:241], v[234:237], v[14:17]
	s_add_i32 s45, s45, 1
	s_cmp_lg_u32 s45, 32
	s_cbranch_scc1 .Lp2_nowrap1
	s_add_i32 s22, s22, 1
	s_cmp_ge_i32 s22, s57
	s_cbranch_scc1 .Lp2_segdone1
	s_mul_i32 s0, s22, s62
	s_add_i32 s1, s0, s86
	s_mul_hi_i32 s0, s1, 0x2aaaaaab
	s_lshr_b32 s2, s0, 31
	s_ashr_i32 s0, s0, 3
	s_add_i32 s0, s0, s2
	s_mul_i32 s2, s0, 48
	s_sub_i32 s2, s1, s2
	s_ashr_i32 s3, s2, 31
	s_ashr_i32 s1, s0, 31
	s_lshl_b64 s[2:3], s[2:3], 20
	s_lshl_b64 s[0:1], s[0:1], 20
	v_readlane_b32 s12, v254, 3
	v_readlane_b32 s13, v254, 4
	s_add_u32 s2, s12, s2
	s_addc_u32 s3, s13, s3
	s_add_u32 s0, s11, s0
	s_addc_u32 s1, s21, s1

.Lp2_nowrap1:
	s_waitcnt vmcnt(0) lgkmcnt(0)
	s_barrier
	s_add_i32 s46, s46, 1
	s_branch .LBB0_167
.Lp2_first:
	ds_read_b128 v[238:241], v177 offset:32768
	global_load_lds_dwordx4 v130, s[14:15]
	s_add_u32 m0, m0, 0x2000
	s_nop 0
	global_load_lds_dwordx4 v132, s[14:15]
	s_add_u32 m0, m0, 0x2000
	s_nop 0
	global_load_lds_dwordx4 v134, s[14:15]
	s_add_u32 m0, m0, 0x2000
	s_nop 0
	global_load_lds_dwordx4 v136, s[14:15]
	s_add_u32 m0, m0, 0x2000
	s_nop 0
	ds_read_b128 v[242:245], v177 offset:34816
	ds_read_b128 v[178:181], v162
	ds_read_b128 v[182:185], v163
	ds_read_b128 v[186:189], v164
	ds_read_b128 v[190:193], v165
	ds_read_b128 v[222:225], v166
	ds_read_b128 v[226:229], v167
	ds_read_b128 v[230:233], v168
	ds_read_b128 v[234:237], v0
	ds_read_b128 v[246:249], v177 offset:36864
	ds_read_b128 v[212:215], v177 offset:38912
	s_branch .Lp2_partb0
.Lp2_epi0:
	s_waitcnt lgkmcnt(0)
	s_nop 7
	s_nop 7
	s_mul_i32 s13, s44, s62
	s_add_i32 s13, s13, s86
	s_cmpk_lt_i32 s13, 0x540
	v_mov_b32_e32 v0, v196
	s_cselect_b64 s[42:43], -1, 0
	s_cmpk_gt_i32 s13, 0x53f
	s_mov_b64 s[6:7], -1
	s_cbranch_scc1 .LBB0_175
	s_mov_b64 s[6:7], 0

.LBB0_301:
	v_cvt_pk_bf16_f32 v2, v2, v3
	v_cvt_pk_bf16_f32 v3, v4, v5
	v_mov_b32_e32 v5, 0
	global_store_dwordx2 v[14:15], v[2:3], off offset:96
	s_add_i32 s44, s44, 1
	s_mov_b32 s6, 0
	v_mov_b32_e32 v4, v5
	v_mov_b32_e32 v3, v5
	v_mov_b32_e32 v2, v5
	v_mov_b32_e32 v9, v5
	v_mov_b32_e32 v8, v5
	v_mov_b32_e32 v7, v5
	v_mov_b32_e32 v6, v5
	v_mov_b32_e32 v13, v5
	v_mov_b32_e32 v12, v5
	v_mov_b32_e32 v11, v5
	v_mov_b32_e32 v10, v5
	v_mov_b32_e32 v17, v5
	v_mov_b32_e32 v16, v5
	v_mov_b32_e32 v15, v5
	v_mov_b32_e32 v14, v5
	v_mov_b32_e32 v21, v5
	v_mov_b32_e32 v20, v5
	v_mov_b32_e32 v19, v5
	v_mov_b32_e32 v18, v5
	v_mov_b32_e32 v25, v5
	v_mov_b32_e32 v24, v5
	v_mov_b32_e32 v23, v5
	v_mov_b32_e32 v22, v5
	v_mov_b32_e32 v29, v5
	v_mov_b32_e32 v28, v5
	v_mov_b32_e32 v27, v5
	v_mov_b32_e32 v26, v5
	v_mov_b32_e32 v33, v5
	v_mov_b32_e32 v32, v5
	v_mov_b32_e32 v31, v5
	v_mov_b32_e32 v30, v5
	v_mov_b32_e32 v37, v5
	v_mov_b32_e32 v36, v5
	v_mov_b32_e32 v35, v5
	v_mov_b32_e32 v34, v5
	v_mov_b32_e32 v41, v5
	v_mov_b32_e32 v40, v5
	v_mov_b32_e32 v39, v5
	v_mov_b32_e32 v38, v5
	v_mov_b32_e32 v45, v5
	v_mov_b32_e32 v44, v5
	v_mov_b32_e32 v43, v5
	v_mov_b32_e32 v42, v5
	v_mov_b32_e32 v49, v5
	v_mov_b32_e32 v48, v5
	v_mov_b32_e32 v47, v5
	v_mov_b32_e32 v46, v5
	v_mov_b32_e32 v53, v5
	v_mov_b32_e32 v52, v5
	v_mov_b32_e32 v51, v5
	v_mov_b32_e32 v50, v5
	v_mov_b32_e32 v57, v5
	v_mov_b32_e32 v56, v5
	v_mov_b32_e32 v55, v5
	v_mov_b32_e32 v54, v5
	v_mov_b32_e32 v61, v5
	v_mov_b32_e32 v60, v5
	v_mov_b32_e32 v59, v5
	v_mov_b32_e32 v58, v5
	v_mov_b32_e32 v65, v5
	v_mov_b32_e32 v64, v5
	v_mov_b32_e32 v63, v5
	v_mov_b32_e32 v62, v5
	v_mov_b32_e32 v69, v5
	v_mov_b32_e32 v68, v5
	v_mov_b32_e32 v67, v5
	v_mov_b32_e32 v66, v5
	v_mov_b32_e32 v73, v5
	v_mov_b32_e32 v72, v5
	v_mov_b32_e32 v71, v5
	v_mov_b32_e32 v70, v5
	v_mov_b32_e32 v77, v5
	v_mov_b32_e32 v76, v5
	v_mov_b32_e32 v75, v5
	v_mov_b32_e32 v74, v5
	v_mov_b32_e32 v81, v5
	v_mov_b32_e32 v80, v5
	v_mov_b32_e32 v79, v5
	v_mov_b32_e32 v78, v5
	v_mov_b32_e32 v85, v5
	v_mov_b32_e32 v84, v5
	v_mov_b32_e32 v83, v5
	v_mov_b32_e32 v82, v5
	v_mov_b32_e32 v89, v5
	v_mov_b32_e32 v88, v5
	v_mov_b32_e32 v87, v5
	v_mov_b32_e32 v86, v5
	v_mov_b32_e32 v93, v5
	v_mov_b32_e32 v92, v5
	v_mov_b32_e32 v91, v5
	v_mov_b32_e32 v90, v5
	v_mov_b32_e32 v97, v5
	v_mov_b32_e32 v96, v5
	v_mov_b32_e32 v95, v5
	v_mov_b32_e32 v94, v5
	v_mov_b32_e32 v101, v5
	v_mov_b32_e32 v100, v5
	v_mov_b32_e32 v99, v5
	v_mov_b32_e32 v98, v5
	v_mov_b32_e32 v105, v5
	v_mov_b32_e32 v104, v5
	v_mov_b32_e32 v103, v5
	v_mov_b32_e32 v102, v5
	v_mov_b32_e32 v109, v5
	v_mov_b32_e32 v108, v5
	v_mov_b32_e32 v107, v5
	v_mov_b32_e32 v106, v5
	v_mov_b32_e32 v113, v5
	v_mov_b32_e32 v112, v5
	v_mov_b32_e32 v111, v5
	v_mov_b32_e32 v110, v5
	v_mov_b32_e32 v117, v5
	v_mov_b32_e32 v116, v5
	v_mov_b32_e32 v115, v5
	v_mov_b32_e32 v114, v5
	v_mov_b32_e32 v121, v5
	v_mov_b32_e32 v120, v5
	v_mov_b32_e32 v119, v5
	v_mov_b32_e32 v118, v5
	v_mov_b32_e32 v125, v5
	v_mov_b32_e32 v124, v5
	v_mov_b32_e32 v123, v5
	v_mov_b32_e32 v122, v5
	v_mov_b32_e32 v129, v5
	v_mov_b32_e32 v128, v5
	v_mov_b32_e32 v127, v5
	v_mov_b32_e32 v126, v5
	v_add_u32_e32 v0, v158, v159
	v_add_u32_e32 v177, v146, v160
	s_lshl_b32 s7, s45, 7
	s_add_u32 s12, s0, s7
	s_addc_u32 s13, s1, 0
	ds_read_b128 v[178:181], v162
	s_waitcnt lgkmcnt(0)
	s_branch .Lp2_cont0
.Lp2_epi1:
	s_waitcnt lgkmcnt(0)
	s_nop 7
	s_nop 7
	s_mul_i32 s13, s44, s62
	s_add_i32 s13, s13, s86
	s_cmpk_lt_i32 s13, 0x540
	v_mov_b32_e32 v0, v196
	s_cselect_b64 s[26:27], -1, 0
	s_cmpk_gt_i32 s13, 0x53f
	s_mov_b64 s[6:7], -1
	s_cbranch_scc1 .LBB0_311
	s_mov_b64 s[6:7], 0

.LBB0_437:
	v_cvt_pk_bf16_f32 v2, v2, v3
	v_cvt_pk_bf16_f32 v3, v4, v5
	v_mov_b32_e32 v5, 0
	global_store_dwordx2 v[14:15], v[2:3], off offset:96
	s_add_i32 s44, s44, 1
	s_mov_b32 s6, 0
	v_mov_b32_e32 v4, v5
	v_mov_b32_e32 v3, v5
	v_mov_b32_e32 v2, v5
	v_mov_b32_e32 v9, v5
	v_mov_b32_e32 v8, v5
	v_mov_b32_e32 v7, v5
	v_mov_b32_e32 v6, v5
	v_mov_b32_e32 v13, v5
	v_mov_b32_e32 v12, v5
	v_mov_b32_e32 v11, v5
	v_mov_b32_e32 v10, v5
	v_mov_b32_e32 v17, v5
	v_mov_b32_e32 v16, v5
	v_mov_b32_e32 v15, v5
	v_mov_b32_e32 v14, v5
	v_mov_b32_e32 v21, v5
	v_mov_b32_e32 v20, v5
	v_mov_b32_e32 v19, v5
	v_mov_b32_e32 v18, v5
	v_mov_b32_e32 v25, v5
	v_mov_b32_e32 v24, v5
	v_mov_b32_e32 v23, v5
	v_mov_b32_e32 v22, v5
	v_mov_b32_e32 v29, v5
	v_mov_b32_e32 v28, v5
	v_mov_b32_e32 v27, v5
	v_mov_b32_e32 v26, v5
	v_mov_b32_e32 v33, v5
	v_mov_b32_e32 v32, v5
	v_mov_b32_e32 v31, v5
	v_mov_b32_e32 v30, v5
	v_mov_b32_e32 v37, v5
	v_mov_b32_e32 v36, v5
	v_mov_b32_e32 v35, v5
	v_mov_b32_e32 v34, v5
	v_mov_b32_e32 v41, v5
	v_mov_b32_e32 v40, v5
	v_mov_b32_e32 v39, v5
	v_mov_b32_e32 v38, v5
	v_mov_b32_e32 v45, v5
	v_mov_b32_e32 v44, v5
	v_mov_b32_e32 v43, v5
	v_mov_b32_e32 v42, v5
	v_mov_b32_e32 v49, v5
	v_mov_b32_e32 v48, v5
	v_mov_b32_e32 v47, v5
	v_mov_b32_e32 v46, v5
	v_mov_b32_e32 v53, v5
	v_mov_b32_e32 v52, v5
	v_mov_b32_e32 v51, v5
	v_mov_b32_e32 v50, v5
	v_mov_b32_e32 v57, v5
	v_mov_b32_e32 v56, v5
	v_mov_b32_e32 v55, v5
	v_mov_b32_e32 v54, v5
	v_mov_b32_e32 v61, v5
	v_mov_b32_e32 v60, v5
	v_mov_b32_e32 v59, v5
	v_mov_b32_e32 v58, v5
	v_mov_b32_e32 v65, v5
	v_mov_b32_e32 v64, v5
	v_mov_b32_e32 v63, v5
	v_mov_b32_e32 v62, v5
	v_mov_b32_e32 v69, v5
	v_mov_b32_e32 v68, v5
	v_mov_b32_e32 v67, v5
	v_mov_b32_e32 v66, v5
	v_mov_b32_e32 v73, v5
	v_mov_b32_e32 v72, v5
	v_mov_b32_e32 v71, v5
	v_mov_b32_e32 v70, v5
	v_mov_b32_e32 v77, v5
	v_mov_b32_e32 v76, v5
	v_mov_b32_e32 v75, v5
	v_mov_b32_e32 v74, v5
	v_mov_b32_e32 v81, v5
	v_mov_b32_e32 v80, v5
	v_mov_b32_e32 v79, v5
	v_mov_b32_e32 v78, v5
	v_mov_b32_e32 v85, v5
	v_mov_b32_e32 v84, v5
	v_mov_b32_e32 v83, v5
	v_mov_b32_e32 v82, v5
	v_mov_b32_e32 v89, v5
	v_mov_b32_e32 v88, v5
	v_mov_b32_e32 v87, v5
	v_mov_b32_e32 v86, v5
	v_mov_b32_e32 v93, v5
	v_mov_b32_e32 v92, v5
	v_mov_b32_e32 v91, v5
	v_mov_b32_e32 v90, v5
	v_mov_b32_e32 v97, v5
	v_mov_b32_e32 v96, v5
	v_mov_b32_e32 v95, v5
	v_mov_b32_e32 v94, v5
	v_mov_b32_e32 v101, v5
	v_mov_b32_e32 v100, v5
	v_mov_b32_e32 v99, v5
	v_mov_b32_e32 v98, v5
	v_mov_b32_e32 v105, v5
	v_mov_b32_e32 v104, v5
	v_mov_b32_e32 v103, v5
	v_mov_b32_e32 v102, v5
	v_mov_b32_e32 v109, v5
	v_mov_b32_e32 v108, v5
	v_mov_b32_e32 v107, v5
	v_mov_b32_e32 v106, v5
	v_mov_b32_e32 v113, v5
	v_mov_b32_e32 v112, v5
	v_mov_b32_e32 v111, v5
	v_mov_b32_e32 v110, v5
	v_mov_b32_e32 v117, v5
	v_mov_b32_e32 v116, v5
	v_mov_b32_e32 v115, v5
	v_mov_b32_e32 v114, v5
	v_mov_b32_e32 v121, v5
	v_mov_b32_e32 v120, v5
	v_mov_b32_e32 v119, v5
	v_mov_b32_e32 v118, v5
	v_mov_b32_e32 v125, v5
	v_mov_b32_e32 v124, v5
	v_mov_b32_e32 v123, v5
	v_mov_b32_e32 v122, v5
	v_mov_b32_e32 v129, v5
	v_mov_b32_e32 v128, v5
	v_mov_b32_e32 v127, v5
	v_mov_b32_e32 v126, v5
	v_add_u32_e32 v0, v161, v157
	s_lshl_b32 s7, s45, 7
	s_add_u32 s12, s0, s7
	s_addc_u32 s13, s1, 0
	ds_read_b128 v[178:181], v169
	s_waitcnt lgkmcnt(0)
	s_branch .Lp2_cont1
.Lp2_exit:
	s_waitcnt vmcnt(0) lgkmcnt(0)
	s_barrier
